# FoX unit prologue: decay-table loads issued before the K/V DMAs, one counted vmcnt(4) wait, straight-line predicated LDS writes (was 2-3 serialized round trips)
# speedup vs baseline: 1.0024x; 1.0024x over previous
;   #define DMA_K(t,slot) glds16(ksrc+(long)(t)*KVBLK*DM,(unsigned)__builtin_amdgcn_readfirstlane(kdst+(slot)))
;   #define DMA_V(t,slot) glds16(vsrc+(long)(t)*KVBLK*DM,(unsigned)__builtin_amdgcn_readfirstlane(vdst+(slot)))
; template<int THRL,int MODE,int DM,bool DRY=false> __device__ __forceinline__ void attn_unit(int b,int h,int qb,const bf16*Q,const bf16*__restrict__ K,const bf16*__restrict__ V,bf16*O,const bf16*__restrict__ Z,const float*__restrict__ XP,const int*__restrict__ TS,volatile unsigned*lw,unsigned nxt,cha ...
;     ...
;     { const int tsv=__builtin_amdgcn_readfirstlane(TS[qb]); tskip=tsv&0xffff; fixedref=(tsv>>16)&1; }
;     ksrc=ksrc_+(long)tskip*KVBLK*DM; vsrc=vsrc_+(long)tskip*KVBLK*DM; NT-=tskip;
;   }
;   const lds_cptr fsl=(lds_cptr)shm+XOFF+16*hi+tskip*256;
;     ...
;   DMA_K(0,0);DMA_V(0,0);DMA_K(1,SLOTB);
;     ...
;   if constexpr(MODE==1){ float*fs=(float*)(shm+XOFF); for(int i=tid+64*tskip;i<q0+QB;i+=NW*64)fs[i]=XP[i]; }
.LBB0_1438:
	s_or_b64 exec, exec, s[8:9]
	s_mul_hi_i32 s8, s10, 0xd5555555
	s_lshr_b32 s9, s8, 31
	s_ashr_i32 s85, s8, 5
	s_mul_hi_i32 s8, s10, 0x2aaaaaab
	s_add_i32 s85, s85, s9
	s_lshr_b32 s9, s8, 31
	s_lshr_b32 s8, s8, 5
	s_add_i32 s8, s8, s9
	s_mulk_i32 s8, 0xc0
	s_sub_i32 s60, s10, s8
	s_sext_i32_i16 s8, s60
	s_mulk_i32 s8, 0x2aab
	s_lshr_b32 s9, s8, 31
	s_ashr_i32 s8, s8, 18
	s_add_i32 s58, s8, s9
	s_mul_i32 s8, s58, 24
	s_sub_i32 s8, s60, s8
	s_sext_i32_i16 s10, s8
	s_lshl_b32 s8, s60, 3
	s_ashr_i32 s9, s8, 31
	s_add_i32 s16, s85, 7
	s_lshl_b64 s[8:9], s[8:9], 2
	s_add_u32 s61, s18, s8
	v_mov_b32_e32 v207, v220
	s_addc_u32 s66, s33, s9
	s_ashr_i32 s59, s58, 31
	v_readfirstlane_b32 s88, v207
	s_ashr_i32 s81, s88, 6
	s_lshl_b64 s[8:9], s[58:59], 11
	s_lshl_b32 s91, s16, 8
	s_add_u32 s8, s8, s91
	s_addc_u32 s9, s9, 0
	s_lshl_b32 s92, s81, 5
	s_ashr_i32 s11, s92, 31
	s_add_u32 s8, s8, s92
	s_addc_u32 s9, s9, s11
	s_mulk_i32 s9, 0x1c00
	s_mul_hi_u32 s11, s8, 0x1c00
	s_add_i32 s9, s11, s9
	s_mulk_i32 s8, 0x1c00
	s_lshl_b64 s[52:53], s[8:9], 1
	s_add_u32 s11, s0, s52
	s_addc_u32 s51, s1, s53
	s_lshl_b32 s8, s10, 6
	s_ashr_i32 s9, s8, 31
	s_lshl_b64 s[54:55], s[8:9], 1
	s_add_u32 s50, s11, s54
	s_addc_u32 s51, s51, s55
	s_mul_i32 s11, s58, 0x1c00000
	s_mul_hi_i32 s10, s58, 0x1c00000
	s_add_u32 s8, s42, s11
	s_addc_u32 s9, s43, s10
	s_add_u32 s8, s8, s54
	s_addc_u32 s9, s9, s55
	s_add_u32 s11, s71, s11
	s_addc_u32 s10, s72, s10
	s_add_u32 s62, s11, s54
	s_addc_u32 s63, s10, s55
	s_ashr_i32 s10, s88, 3
	s_lshl_b32 s56, s81, 3
	s_andn2_b32 s10, s10, 31
	s_ashr_i32 s57, s56, 31
	s_lshl_b32 s67, s81, 4
	s_ashr_i32 s11, s10, 31
	s_lshl_b32 s59, s81, 10
	s_cmp_lg_u32 0, -1
	s_cselect_b32 s64, 0, 0
	s_add_i32 s83, s59, s64
	s_add_i32 s84, s83, 0x6000
	s_add_i32 s90, s91, 0x100
	s_lshl_b64 s[64:65], s[16:17], 2
	s_add_u32 s64, s61, s64
	s_addc_u32 s65, s66, s65
	v_mov_b64_e32 v[0:1], s[64:65]
	s_sub_u32 s98, s64, s18
	s_add_u32 s98, s98, 0x18000
	v_mov_b32_e32 v6, s98
	ds_read_b32 v6, v6
	v_and_b32_e32 v208, 31, v207
	v_mul_u32_u24_e32 v0, 0x1c00, v208
	v_bfe_u32 v209, v207, 5, 1
	v_lshlrev_b32_e32 v0, 1, v0
	v_lshl_or_b32 v192, v209, 4, v0
	v_lshl_add_u64 v[0:1], s[50:51], 0, v[192:193]
	global_load_dwordx4 v[108:111], v[0:1], off
	global_load_dwordx4 v[104:107], v[0:1], off offset:32
	global_load_dwordx4 v[100:103], v[0:1], off offset:64
	global_load_dwordx4 v[96:99], v[0:1], off offset:96
	v_bfe_u32 v4, v207, 2, 4
	v_and_b32_e32 v210, 63, v207
	v_and_or_b32 v4, s67, 48, v4
	v_mul_u32_u24_e32 v2, 0x1c00, v210
	v_mul_u32_u24_e32 v4, 0x1c00, v4
	v_mov_b32_e32 v173, v193
	v_lshlrev_b32_e32 v212, 3, v207
	v_lshlrev_b32_e32 v192, 1, v2
	v_lshlrev_b32_e32 v172, 1, v4
	v_and_b32_e32 v211, 24, v212
	v_lshl_add_u64 v[2:3], s[8:9], 0, v[192:193]
	v_lshl_add_u64 v[4:5], s[62:63], 0, v[172:173]
	v_mov_b32_e32 v1, v193
	v_lshlrev_b32_e32 v0, 1, v211
	v_lshl_add_u64 v[2:3], s[56:57], 1, v[2:3]
	v_lshl_add_u64 v[4:5], s[10:11], 1, v[4:5]
	v_lshl_add_u64 v[0:1], v[4:5], 0, v[0:1]
	s_add_i32 s61, s83, 0x2000
	s_waitcnt lgkmcnt(0)
	v_readfirstlane_b32 s89, v6
	s_and_b32 s87, s89, 0xffff
	s_lshl_b32 s16, s87, 6
	s_mov_b32 s98, s60
	s_ashr_i32 s99, s60, 31
	s_lshl_b64 s[98:99], s[98:99], 13
	s_add_u32 s98, s4, s98
	s_addc_u32 s99, s5, s99
	v_add_u32_e32 v8, s16, v207
	v_lshlrev_b32_e32 v12, 2, v8
	v_add_u32_e32 v13, 0x1000, v12
	v_add_u32_e32 v9, 0x200, v8
	v_add_u32_e32 v10, 0x400, v8
	v_add_u32_e32 v11, 0x600, v8
	v_cmp_gt_i32_e32 vcc, s90, v8
	s_and_saveexec_b64 s[100:101], vcc
	global_load_dword v14, v12, s[98:99]
	v_cmp_gt_i32_e32 vcc, s90, v9
	s_and_b64 exec, exec, vcc
	global_load_dword v15, v12, s[98:99] offset:2048
	v_cmp_gt_i32_e32 vcc, s90, v10
	s_and_b64 exec, exec, vcc
	global_load_dword v16, v13, s[98:99]
	v_cmp_gt_i32_e32 vcc, s90, v11
	s_and_b64 exec, exec, vcc
	global_load_dword v17, v13, s[98:99] offset:2048
	s_mov_b64 exec, s[100:101]
	v_mad_u64_u32 v[66:67], s[8:9], s16, v204, v[2:3]
	s_mov_b32 s8, m0
	s_mov_b32 m0, s83
	s_nop 0
	global_load_lds_dwordx4 v[66:67], off
	s_mov_b32 m0, s8
	v_lshl_add_u64 v[2:3], v[66:67], 0, s[24:25]
	v_mad_u64_u32 v[64:65], s[8:9], s16, v204, v[0:1]
	s_mov_b32 s8, m0
	s_mov_b32 m0, s84
	s_nop 0
	global_load_lds_dwordx4 v[64:65], off
	s_mov_b32 m0, s8
	v_lshl_add_u64 v[0:1], v[66:67], 0, s[22:23]
	s_mov_b32 s8, m0
	s_mov_b32 m0, s61
	s_nop 0
	global_load_lds_dwordx4 v[0:1], off
	s_mov_b32 m0, s8
	s_add_i32 s8, s83, 0x4000
	s_mov_b32 s9, m0
	s_mov_b32 m0, s8
	s_nop 0
	global_load_lds_dwordx4 v[2:3], off
	s_mov_b32 m0, s9
	s_lshl_b32 s86, s87, 8
	s_waitcnt vmcnt(4)
	v_add_u32_e32 v18, 0x15000, v12
	v_cmp_gt_i32_e32 vcc, s90, v8
	s_and_saveexec_b64 s[100:101], vcc
	ds_write_b32 v18, v14
	v_cmp_gt_i32_e32 vcc, s90, v9
	s_and_b64 exec, exec, vcc
	ds_write_b32 v18, v15 offset:2048
	v_cmp_gt_i32_e32 vcc, s90, v10
	s_and_b64 exec, exec, vcc
	ds_write_b32 v18, v16 offset:4096
	v_cmp_gt_i32_e32 vcc, s90, v11
	s_and_b64 exec, exec, vcc
	ds_write_b32 v18, v17 offset:6144
	s_mov_b64 exec, s[100:101]
